# grid barrier: non-leaders poll the cross-XCD generation directly (acquire invalidate after the poll) instead of the per-XCD forwarded word with hoisted invalidate
# baseline (speedup 1.0000x reference)
; __device__ __forceinline__ unsigned xb_ld(unsigned* p)              { return __hip_atomic_load(p, __ATOMIC_RELAXED, __HIP_MEMORY_SCOPE_AGENT); }
; __device__ __forceinline__ unsigned xb_add(unsigned* p, unsigned v) { return __hip_atomic_fetch_add(p, v, __ATOMIC_RELAXED, __HIP_MEMORY_SCOPE_AGENT); }
; #define XB_SPIN(cond, bar) do { unsigned _sp = 0; while (cond) { __builtin_amdgcn_s_sleep(1); \
;     if ((++_sp & 255u) == 0u) { if (xb_ld(&(bar)[XB_TMO])) break; if (_sp > XB_SPIN_CAP) { atomicAdd(&(bar)[XB_TMO], 1u); break; } } } } while (0)
; __device__ __forceinline__ void xcd_barrier(const XcdBarrier& b) {
;     ...
;         const unsigned old = xb_add(&bar[XB_XSUB(b.x)], 1u);
;         const unsigned gen = old / nloc;
;         if (old + 1u == (gen + 1u) * nloc) {
;             __builtin_amdgcn_fence(__ATOMIC_RELEASE, "agent");
;             asm volatile("s_waitcnt vmcnt(0)" ::: "memory");
;             const unsigned og = xb_add(&bar[XB_TOP], 1u);
;             const unsigned tg = og / nx;
;             if (og + 1u == (tg + 1u) * nx) xb_add(&bar[XB_TOPGEN], 1u);
;             else XB_SPIN(xb_ld(&bar[XB_TOPGEN]) == tg, bar);
;             __builtin_amdgcn_fence(__ATOMIC_ACQUIRE, "agent");
;             xb_add(&bar[XB_XGEN(b.x)], 1u);
;             asm volatile("s_waitcnt vmcnt(0)" ::: "memory");
;         } else {
;             XB_SPIN(xb_ld(&bar[XB_XGEN(b.x)]) == gen, bar);
;             __builtin_amdgcn_fence(__ATOMIC_ACQUIRE, "agent");
;             asm volatile("s_waitcnt vmcnt(0)" ::: "memory");
;         }
.LBB0_270:
	v_readlane_b32 s6, v255, 3
	v_readlane_b32 s7, v255, 4
	v_mov_b32_e32 v1, 1
	s_nop 0
	v_mov_b64_e32 v[6:7], s[6:7]
	flat_atomic_add v5, v[6:7], v1 sc0
	v_cvt_f32_u32_e32 v1, v4
	v_sub_u32_e32 v6, 0, v4
	v_rcp_iflag_f32_e32 v1, v1
	s_nop 0
	v_mul_f32_e32 v1, 0x4f7ffffe, v1
	v_cvt_u32_f32_e32 v1, v1
	v_mul_lo_u32 v6, v6, v1
	v_mul_hi_u32 v6, v1, v6
	v_add_u32_e32 v1, v1, v6
	s_waitcnt vmcnt(0) lgkmcnt(0)
	v_mul_hi_u32 v1, v5, v1
	v_mul_lo_u32 v6, v1, v4
	v_sub_u32_e32 v6, v5, v6
	v_cmp_ge_u32_e32 vcc, v6, v4
	v_add_u32_e32 v7, 1, v1
	s_nop 0
	v_cndmask_b32_e32 v1, v1, v7, vcc
	v_sub_u32_e32 v7, v6, v4
	v_cndmask_b32_e32 v6, v6, v7, vcc
	v_cmp_ge_u32_e32 vcc, v6, v4
	v_add_u32_e32 v6, 1, v1
	s_nop 0
	v_cndmask_b32_e32 v1, v1, v6, vcc
	v_add_u32_e32 v6, 1, v5
	v_mad_u64_u32 v[4:5], s[6:7], v4, v1, v[4:5]
	v_cmp_ne_u32_e32 vcc, v6, v4
	s_and_saveexec_b64 s[6:7], vcc
	s_xor_b64 s[16:17], exec, s[6:7]
	s_cbranch_execz .LBB0_283
	v_readlane_b32 s6, v255, 9
	v_readlane_b32 s7, v255, 10
	s_nop 1
	v_mov_b64_e32 v[4:5], s[6:7]
	flat_load_dword v2, v[4:5] sc1
	s_waitcnt vmcnt(0) lgkmcnt(0)
	v_cmp_eq_u32_e32 vcc, v2, v1
	s_and_saveexec_b64 s[20:21], vcc
	s_cbranch_execz .LBB0_282
	s_mov_b32 s5, 1
	s_mov_b64 s[22:23], 0
	s_branch .LBB0_274

; __device__ __forceinline__ unsigned xb_ld(unsigned* p)              { return __hip_atomic_load(p, __ATOMIC_RELAXED, __HIP_MEMORY_SCOPE_AGENT); }
; #define XB_SPIN(cond, bar) do { unsigned _sp = 0; while (cond) { __builtin_amdgcn_s_sleep(1); \
;     if ((++_sp & 255u) == 0u) { if (xb_ld(&(bar)[XB_TMO])) break; if (_sp > XB_SPIN_CAP) { atomicAdd(&(bar)[XB_TMO], 1u); break; } } } } while (0)
; __device__ __forceinline__ void xcd_barrier(const XcdBarrier& b) {
;     ...
;             XB_SPIN(xb_ld(&bar[XB_XGEN(b.x)]) == gen, bar);
;             __builtin_amdgcn_fence(__ATOMIC_ACQUIRE, "agent");
.LBB0_278:
	s_andn2_b64 s[6:7], s[26:27], exec
	s_and_b64 s[8:9], s[40:41], exec
	s_or_b64 s[26:27], s[6:7], s[8:9]
	s_and_saveexec_b64 s[40:41], s[38:39]
	s_cbranch_execz .LBB0_273
	v_readlane_b32 s6, v255, 9
	v_readlane_b32 s7, v255, 10
	s_add_i32 s5, s5, 1
	s_or_b64 s[26:27], s[26:27], exec
	v_mov_b64_e32 v[4:5], s[6:7]
	flat_load_dword v2, v[4:5] sc1
	s_waitcnt vmcnt(0) lgkmcnt(0)
	v_cmp_ne_u32_e32 vcc, v2, v1
	s_orn2_b64 s[36:37], vcc, exec
	s_branch .LBB0_273

; __device__ __forceinline__ unsigned xb_ld(unsigned* p)              { return __hip_atomic_load(p, __ATOMIC_RELAXED, __HIP_MEMORY_SCOPE_AGENT); }
; __device__ __forceinline__ unsigned xb_add(unsigned* p, unsigned v) { return __hip_atomic_fetch_add(p, v, __ATOMIC_RELAXED, __HIP_MEMORY_SCOPE_AGENT); }
; #define XB_SPIN(cond, bar) do { unsigned _sp = 0; while (cond) { __builtin_amdgcn_s_sleep(1); \
;     if ((++_sp & 255u) == 0u) { if (xb_ld(&(bar)[XB_TMO])) break; if (_sp > XB_SPIN_CAP) { atomicAdd(&(bar)[XB_TMO], 1u); break; } } } } while (0)
; __device__ __forceinline__ void xcd_barrier(const XcdBarrier& b) {
;     ...
;         const unsigned old = xb_add(&bar[XB_XSUB(b.x)], 1u);
;         const unsigned gen = old / nloc;
;         if (old + 1u == (gen + 1u) * nloc) {
;             __builtin_amdgcn_fence(__ATOMIC_RELEASE, "agent");
;             asm volatile("s_waitcnt vmcnt(0)" ::: "memory");
;             const unsigned og = xb_add(&bar[XB_TOP], 1u);
;             const unsigned tg = og / nx;
;             if (og + 1u == (tg + 1u) * nx) xb_add(&bar[XB_TOPGEN], 1u);
;             else XB_SPIN(xb_ld(&bar[XB_TOPGEN]) == tg, bar);
;             __builtin_amdgcn_fence(__ATOMIC_ACQUIRE, "agent");
;             xb_add(&bar[XB_XGEN(b.x)], 1u);
;             asm volatile("s_waitcnt vmcnt(0)" ::: "memory");
;         } else {
;             XB_SPIN(xb_ld(&bar[XB_XGEN(b.x)]) == gen, bar);
;             __builtin_amdgcn_fence(__ATOMIC_ACQUIRE, "agent");
;             asm volatile("s_waitcnt vmcnt(0)" ::: "memory");
;         }
.LBB0_514:
	v_readlane_b32 s6, v255, 3
	v_readlane_b32 s7, v255, 4
	v_mov_b32_e32 v1, 1
	s_nop 0
	v_mov_b64_e32 v[6:7], s[6:7]
	flat_atomic_add v5, v[6:7], v1 sc0
	v_cvt_f32_u32_e32 v1, v4
	v_sub_u32_e32 v6, 0, v4
	v_rcp_iflag_f32_e32 v1, v1
	s_nop 0
	v_mul_f32_e32 v1, 0x4f7ffffe, v1
	v_cvt_u32_f32_e32 v1, v1
	v_mul_lo_u32 v6, v6, v1
	v_mul_hi_u32 v6, v1, v6
	v_add_u32_e32 v1, v1, v6
	s_waitcnt vmcnt(0) lgkmcnt(0)
	v_mul_hi_u32 v1, v5, v1
	v_mul_lo_u32 v6, v1, v4
	v_sub_u32_e32 v6, v5, v6
	v_cmp_ge_u32_e32 vcc, v6, v4
	v_add_u32_e32 v7, 1, v1
	s_nop 0
	v_cndmask_b32_e32 v1, v1, v7, vcc
	v_sub_u32_e32 v7, v6, v4
	v_cndmask_b32_e32 v6, v6, v7, vcc
	v_cmp_ge_u32_e32 vcc, v6, v4
	v_add_u32_e32 v6, 1, v1
	s_nop 0
	v_cndmask_b32_e32 v1, v1, v6, vcc
	v_add_u32_e32 v6, 1, v5
	v_mad_u64_u32 v[4:5], s[6:7], v4, v1, v[4:5]
	v_readfirstlane_b32 s5, v1
	s_nop 1
	v_writelane_b32 v255, s5, 34
	v_cmp_ne_u32_e32 vcc, v6, v4
	s_and_saveexec_b64 s[6:7], vcc
	s_xor_b64 s[16:17], exec, s[6:7]
	s_cbranch_execz .LBB0_527
	s_branch .LBB0_527
	v_readlane_b32 s6, v255, 9
	v_readlane_b32 s7, v255, 10
	s_nop 1
	v_mov_b64_e32 v[4:5], s[6:7]
	flat_load_dword v2, v[4:5] sc1
	s_waitcnt vmcnt(0) lgkmcnt(0)
	v_cmp_eq_u32_e32 vcc, v2, v1
	s_and_saveexec_b64 s[20:21], vcc
	s_cbranch_execz .LBB0_526
	s_mov_b32 s5, 1
	s_mov_b64 s[22:23], 0
	s_branch .LBB0_518

; __device__ __forceinline__ unsigned xb_ld(unsigned* p)              { return __hip_atomic_load(p, __ATOMIC_RELAXED, __HIP_MEMORY_SCOPE_AGENT); }
; __device__ __forceinline__ unsigned xb_add(unsigned* p, unsigned v) { return __hip_atomic_fetch_add(p, v, __ATOMIC_RELAXED, __HIP_MEMORY_SCOPE_AGENT); }
; #define XB_SPIN(cond, bar) do { unsigned _sp = 0; while (cond) { __builtin_amdgcn_s_sleep(1); \
;     if ((++_sp & 255u) == 0u) { if (xb_ld(&(bar)[XB_TMO])) break; if (_sp > XB_SPIN_CAP) { atomicAdd(&(bar)[XB_TMO], 1u); break; } } } } while (0)
; __device__ __forceinline__ void xcd_barrier(const XcdBarrier& b) {
;     ...
;         const unsigned old = xb_add(&bar[XB_XSUB(b.x)], 1u);
;         const unsigned gen = old / nloc;
;         if (old + 1u == (gen + 1u) * nloc) {
;             __builtin_amdgcn_fence(__ATOMIC_RELEASE, "agent");
;             asm volatile("s_waitcnt vmcnt(0)" ::: "memory");
;             const unsigned og = xb_add(&bar[XB_TOP], 1u);
;             const unsigned tg = og / nx;
;             if (og + 1u == (tg + 1u) * nx) xb_add(&bar[XB_TOPGEN], 1u);
;             else XB_SPIN(xb_ld(&bar[XB_TOPGEN]) == tg, bar);
;             __builtin_amdgcn_fence(__ATOMIC_ACQUIRE, "agent");
;             xb_add(&bar[XB_XGEN(b.x)], 1u);
;             asm volatile("s_waitcnt vmcnt(0)" ::: "memory");
;         } else {
;             XB_SPIN(xb_ld(&bar[XB_XGEN(b.x)]) == gen, bar);
;             __builtin_amdgcn_fence(__ATOMIC_ACQUIRE, "agent");
;             asm volatile("s_waitcnt vmcnt(0)" ::: "memory");
;         }
.LBB0_1996:
	v_readlane_b32 s6, v255, 3
	v_readlane_b32 s7, v255, 4
	v_mov_b32_e32 v1, 1
	s_nop 0
	v_mov_b64_e32 v[6:7], s[6:7]
	flat_atomic_add v5, v[6:7], v1 sc0
	v_cvt_f32_u32_e32 v1, v4
	v_sub_u32_e32 v6, 0, v4
	v_rcp_iflag_f32_e32 v1, v1
	s_nop 0
	v_mul_f32_e32 v1, 0x4f7ffffe, v1
	v_cvt_u32_f32_e32 v1, v1
	v_mul_lo_u32 v6, v6, v1
	v_mul_hi_u32 v6, v1, v6
	v_add_u32_e32 v1, v1, v6
	s_waitcnt vmcnt(0) lgkmcnt(0)
	v_mul_hi_u32 v1, v5, v1
	v_mul_lo_u32 v6, v1, v4
	v_sub_u32_e32 v6, v5, v6
	v_cmp_ge_u32_e32 vcc, v6, v4
	v_add_u32_e32 v7, 1, v1
	s_nop 0
	v_cndmask_b32_e32 v1, v1, v7, vcc
	v_sub_u32_e32 v7, v6, v4
	v_cndmask_b32_e32 v6, v6, v7, vcc
	v_cmp_ge_u32_e32 vcc, v6, v4
	v_add_u32_e32 v6, 1, v1
	s_nop 0
	v_cndmask_b32_e32 v1, v1, v6, vcc
	v_add_u32_e32 v6, 1, v5
	v_mad_u64_u32 v[4:5], s[6:7], v4, v1, v[4:5]
	v_cmp_ne_u32_e32 vcc, v6, v4
	s_and_saveexec_b64 s[6:7], vcc
	s_xor_b64 s[14:15], exec, s[6:7]
	s_cbranch_execz .LBB0_2009
	v_readlane_b32 s6, v255, 9
	v_readlane_b32 s7, v255, 10
	s_nop 1
	v_mov_b64_e32 v[4:5], s[6:7]
	flat_load_dword v2, v[4:5] sc1
	s_waitcnt vmcnt(0) lgkmcnt(0)
	v_cmp_eq_u32_e32 vcc, v2, v1
	s_and_saveexec_b64 s[16:17], vcc
	s_cbranch_execz .LBB0_2008
	s_mov_b32 s5, 1
	s_mov_b64 s[20:21], 0
	s_branch .LBB0_2000

; __device__ __forceinline__ unsigned xb_ld(unsigned* p)              { return __hip_atomic_load(p, __ATOMIC_RELAXED, __HIP_MEMORY_SCOPE_AGENT); }
; #define XB_SPIN(cond, bar) do { unsigned _sp = 0; while (cond) { __builtin_amdgcn_s_sleep(1); \
;     if ((++_sp & 255u) == 0u) { if (xb_ld(&(bar)[XB_TMO])) break; if (_sp > XB_SPIN_CAP) { atomicAdd(&(bar)[XB_TMO], 1u); break; } } } } while (0)
; __device__ __forceinline__ void xcd_barrier(const XcdBarrier& b) {
;     ...
;             XB_SPIN(xb_ld(&bar[XB_XGEN(b.x)]) == gen, bar);
;             __builtin_amdgcn_fence(__ATOMIC_ACQUIRE, "agent");
.LBB0_2004:
	s_andn2_b64 s[6:7], s[24:25], exec
	s_and_b64 s[8:9], s[38:39], exec
	s_or_b64 s[24:25], s[6:7], s[8:9]
	s_and_saveexec_b64 s[38:39], s[36:37]
	s_cbranch_execz .LBB0_1999
	v_readlane_b32 s6, v255, 9
	v_readlane_b32 s7, v255, 10
	s_add_i32 s5, s5, 1
	s_or_b64 s[24:25], s[24:25], exec
	v_mov_b64_e32 v[4:5], s[6:7]
	flat_load_dword v2, v[4:5] sc1
	s_waitcnt vmcnt(0) lgkmcnt(0)
	v_cmp_ne_u32_e32 vcc, v2, v1
	s_orn2_b64 s[26:27], vcc, exec
	s_branch .LBB0_1999

; __device__ __forceinline__ unsigned xb_ld(unsigned* p)              { return __hip_atomic_load(p, __ATOMIC_RELAXED, __HIP_MEMORY_SCOPE_AGENT); }
; __device__ __forceinline__ unsigned xb_add(unsigned* p, unsigned v) { return __hip_atomic_fetch_add(p, v, __ATOMIC_RELAXED, __HIP_MEMORY_SCOPE_AGENT); }
; #define XB_SPIN(cond, bar) do { unsigned _sp = 0; while (cond) { __builtin_amdgcn_s_sleep(1); \
;     if ((++_sp & 255u) == 0u) { if (xb_ld(&(bar)[XB_TMO])) break; if (_sp > XB_SPIN_CAP) { atomicAdd(&(bar)[XB_TMO], 1u); break; } } } } while (0)
; __device__ __forceinline__ void xcd_barrier(const XcdBarrier& b) {
;     ...
;         const unsigned old = xb_add(&bar[XB_XSUB(b.x)], 1u);
;         const unsigned gen = old / nloc;
;         if (old + 1u == (gen + 1u) * nloc) {
;             __builtin_amdgcn_fence(__ATOMIC_RELEASE, "agent");
;             asm volatile("s_waitcnt vmcnt(0)" ::: "memory");
;             const unsigned og = xb_add(&bar[XB_TOP], 1u);
;             const unsigned tg = og / nx;
;             if (og + 1u == (tg + 1u) * nx) xb_add(&bar[XB_TOPGEN], 1u);
;             else XB_SPIN(xb_ld(&bar[XB_TOPGEN]) == tg, bar);
;             __builtin_amdgcn_fence(__ATOMIC_ACQUIRE, "agent");
;             xb_add(&bar[XB_XGEN(b.x)], 1u);
;             asm volatile("s_waitcnt vmcnt(0)" ::: "memory");
;         } else {
;             XB_SPIN(xb_ld(&bar[XB_XGEN(b.x)]) == gen, bar);
;             __builtin_amdgcn_fence(__ATOMIC_ACQUIRE, "agent");
;             asm volatile("s_waitcnt vmcnt(0)" ::: "memory");
;         }
.LBB0_2259:
	v_readlane_b32 s4, v255, 3
	v_readlane_b32 s5, v255, 4
	v_mov_b32_e32 v1, 1
	s_nop 0
	v_mov_b64_e32 v[6:7], s[4:5]
	flat_atomic_add v5, v[6:7], v1 sc0
	v_cvt_f32_u32_e32 v1, v4
	v_sub_u32_e32 v6, 0, v4
	v_rcp_iflag_f32_e32 v1, v1
	s_nop 0
	v_mul_f32_e32 v1, 0x4f7ffffe, v1
	v_cvt_u32_f32_e32 v1, v1
	v_mul_lo_u32 v6, v6, v1
	v_mul_hi_u32 v6, v1, v6
	v_add_u32_e32 v1, v1, v6
	s_waitcnt vmcnt(0) lgkmcnt(0)
	v_mul_hi_u32 v1, v5, v1
	v_mul_lo_u32 v6, v1, v4
	v_sub_u32_e32 v6, v5, v6
	v_cmp_ge_u32_e32 vcc, v6, v4
	v_add_u32_e32 v7, 1, v1
	s_nop 0
	v_cndmask_b32_e32 v1, v1, v7, vcc
	v_sub_u32_e32 v7, v6, v4
	v_cndmask_b32_e32 v6, v6, v7, vcc
	v_cmp_ge_u32_e32 vcc, v6, v4
	v_add_u32_e32 v6, 1, v1
	s_nop 0
	v_cndmask_b32_e32 v1, v1, v6, vcc
	v_add_u32_e32 v6, 1, v5
	v_mad_u64_u32 v[4:5], s[4:5], v4, v1, v[4:5]
	v_cmp_ne_u32_e32 vcc, v6, v4
	s_and_saveexec_b64 s[4:5], vcc
	s_xor_b64 s[14:15], exec, s[4:5]
	s_cbranch_execz .LBB0_2272
	v_readlane_b32 s4, v255, 9
	v_readlane_b32 s5, v255, 10
	s_nop 1
	v_mov_b64_e32 v[4:5], s[4:5]
	flat_load_dword v2, v[4:5] sc1
	s_waitcnt vmcnt(0) lgkmcnt(0)
	v_cmp_eq_u32_e32 vcc, v2, v1
	s_and_saveexec_b64 s[16:17], vcc
	s_cbranch_execz .LBB0_2271
	s_mov_b32 s4, 1
	s_mov_b64 s[20:21], 0
	s_branch .LBB0_2263

; __device__ __forceinline__ unsigned xb_ld(unsigned* p)              { return __hip_atomic_load(p, __ATOMIC_RELAXED, __HIP_MEMORY_SCOPE_AGENT); }
; #define XB_SPIN(cond, bar) do { unsigned _sp = 0; while (cond) { __builtin_amdgcn_s_sleep(1); \
;     if ((++_sp & 255u) == 0u) { if (xb_ld(&(bar)[XB_TMO])) break; if (_sp > XB_SPIN_CAP) { atomicAdd(&(bar)[XB_TMO], 1u); break; } } } } while (0)
; __device__ __forceinline__ void xcd_barrier(const XcdBarrier& b) {
;     ...
;             XB_SPIN(xb_ld(&bar[XB_XGEN(b.x)]) == gen, bar);
;             __builtin_amdgcn_fence(__ATOMIC_ACQUIRE, "agent");
.LBB0_2267:
	s_andn2_b64 s[6:7], s[24:25], exec
	s_and_b64 s[8:9], s[38:39], exec
	s_or_b64 s[24:25], s[6:7], s[8:9]
	s_and_saveexec_b64 s[38:39], s[36:37]
	s_cbranch_execz .LBB0_2262
	v_readlane_b32 s6, v255, 9
	v_readlane_b32 s7, v255, 10
	s_add_i32 s4, s4, 1
	s_or_b64 s[24:25], s[24:25], exec
	v_mov_b64_e32 v[4:5], s[6:7]
	flat_load_dword v2, v[4:5] sc1
	s_waitcnt vmcnt(0) lgkmcnt(0)
	v_cmp_ne_u32_e32 vcc, v2, v1
	s_orn2_b64 s[26:27], vcc, exec
	s_branch .LBB0_2262
